# norm phases: rows 1-3 residual/D loads of each 4-row batch prefetched right after row 0's loads (one exposed round trip per batch instead of eight); sgu epilogue u-loads batched
# speedup vs baseline: 1.0122x; 1.0122x over previous
.LBB0_289:
	s_waitcnt vmcnt(1)
	v_lshl_add_u64 v[24:25], v[44:45], 0, s[2:3]
	global_load_dwordx2 v[26:27], v[24:25], off offset:-64
	global_load_dword v20, v[46:47], off
	global_load_dwordx2 v[110:111], v[24:25], off offset:-32
	global_load_dwordx2 v[112:113], v[24:25], off
	global_load_dwordx2 v[114:115], v[24:25], off offset:32
	v_mov_b32_e32 v132, v16
	s_waitcnt vmcnt(5)
	v_lshl_add_u64 v[22:23], v[42:43], 0, s[2:3]
	s_mov_b64 s[8:9], 0x8000
	s_add_u32 s2, s2, 0x80
	v_lshl_add_u64 v[48:49], v[48:49], 0, s[8:9]
	s_mov_b64 s[8:9], 0x200
	s_addc_u32 s3, s3, 0
	v_lshl_add_u64 v[46:47], v[46:47], 0, s[8:9]
	v_add_u32_e32 v37, 0x4200, v37
	s_cmpk_lg_i32 s2, 0x200
	s_waitcnt vmcnt(4)
	v_lshlrev_b32_e32 v57, 16, v26
	v_mul_f32_e32 v21, 0x3d372713, v57
	v_mul_f32_e32 v21, v21, v57
	v_fma_f32 v21, v21, v57, v57
	v_mul_f32_e32 v21, 0x3f4c422a, v21
	v_add_f32_e32 v21, v21, v21
	v_mul_f32_e32 v21, 0x3fb8aa3b, v21
	v_exp_f32_e32 v21, v21
	v_mul_f32_e32 v57, 0.5, v57
	v_add_f32_e32 v21, 1.0, v21
	v_rcp_f32_e32 v21, v21
	s_nop 0
	v_fma_f32 v21, v21, -2.0, 1.0
	s_waitcnt vmcnt(3)
	v_pk_add_f32 v[58:59], v[20:21], v[132:133]
	v_mov_b32_e32 v132, v17
	v_mul_f32_e32 v16, v57, v59
	v_mul_f32_e32 v57, v58, v16
	v_and_b32_e32 v16, 0xffff0000, v26
	v_mul_f32_e32 v21, 0x3d372713, v16
	v_mul_f32_e32 v21, v21, v16
	v_fma_f32 v21, v21, v16, v16
	v_mul_f32_e32 v21, 0x3f4c422a, v21
	v_add_f32_e32 v21, v21, v21
	v_mul_f32_e32 v21, 0x3fb8aa3b, v21
	v_exp_f32_e32 v21, v21
	v_mul_f32_e32 v26, 0.5, v16
	v_add_f32_e32 v21, 1.0, v21
	v_rcp_f32_e32 v21, v21
	s_nop 0
	v_fma_f32 v21, v21, -2.0, 1.0
	v_pk_add_f32 v[16:17], v[20:21], v[132:133]
	v_mov_b32_e32 v132, v18
	v_mul_f32_e32 v17, v26, v17
	v_mul_f32_e32 v16, v16, v17
	v_lshlrev_b32_e32 v17, 16, v27
	v_mul_f32_e32 v21, 0x3d372713, v17
	v_mul_f32_e32 v21, v21, v17
	v_fma_f32 v21, v21, v17, v17
	v_mul_f32_e32 v21, 0x3f4c422a, v21
	v_add_f32_e32 v21, v21, v21
	v_mul_f32_e32 v21, 0x3fb8aa3b, v21
	v_exp_f32_e32 v21, v21
	v_and_b32_e32 v18, 0xffff0000, v27
	v_mul_f32_e32 v17, 0.5, v17
	v_mul_f32_e32 v26, 0.5, v18
	v_add_f32_e32 v21, 1.0, v21
	v_rcp_f32_e32 v21, v21
	v_cvt_pk_bf16_f32 v16, v57, v16
	s_nop 0
	v_fma_f32 v21, v21, -2.0, 1.0
	v_pk_add_f32 v[58:59], v[20:21], v[132:133]
	v_mul_f32_e32 v21, 0x3d372713, v18
	v_mul_f32_e32 v21, v21, v18
	v_fma_f32 v21, v21, v18, v18
	v_mul_f32_e32 v21, 0x3f4c422a, v21
	v_add_f32_e32 v21, v21, v21
	v_mul_f32_e32 v21, 0x3fb8aa3b, v21
	v_exp_f32_e32 v21, v21
	v_mov_b32_e32 v132, v19
	v_mul_f32_e32 v17, v17, v59
	v_mul_f32_e32 v17, v58, v17
	v_add_f32_e32 v21, 1.0, v21
	v_rcp_f32_e32 v21, v21
	s_nop 0
	v_fma_f32 v21, v21, -2.0, 1.0
	v_pk_add_f32 v[18:19], v[20:21], v[132:133]
	v_mov_b32_e32 v132, v12
	v_mul_f32_e32 v19, v26, v19
	v_mul_f32_e32 v18, v18, v19
	v_cvt_pk_bf16_f32 v17, v17, v18
	global_store_dwordx2 v[22:23], v[16:17], off offset:1536
	s_waitcnt vmcnt(3)
	v_mov_b32_e32 v16, v110
	v_mov_b32_e32 v17, v111
	v_lshlrev_b32_e32 v18, 16, v16
	v_mul_f32_e32 v19, 0x3d372713, v18
	v_mul_f32_e32 v19, v19, v18
	v_fma_f32 v19, v19, v18, v18
	v_mul_f32_e32 v19, 0x3f4c422a, v19
	v_add_f32_e32 v19, v19, v19
	v_mul_f32_e32 v19, 0x3fb8aa3b, v19
	v_exp_f32_e32 v19, v19
	v_mul_f32_e32 v26, 0.5, v18
	v_add_f32_e32 v19, 1.0, v19
	v_rcp_f32_e32 v19, v19
	s_nop 0
	v_fma_f32 v21, v19, -2.0, 1.0
	v_pk_add_f32 v[18:19], v[20:21], v[132:133]
	v_mov_b32_e32 v132, v13
	v_mul_f32_e32 v12, v26, v19
	v_mul_f32_e32 v18, v18, v12
	v_and_b32_e32 v12, 0xffff0000, v16
	v_mul_f32_e32 v16, 0x3d372713, v12
	v_mul_f32_e32 v16, v16, v12
	v_fma_f32 v16, v16, v12, v12
	v_mul_f32_e32 v16, 0x3f4c422a, v16
	v_add_f32_e32 v16, v16, v16
	v_mul_f32_e32 v16, 0x3fb8aa3b, v16
	v_exp_f32_e32 v16, v16
	s_nop 0
	v_add_f32_e32 v16, 1.0, v16
	v_rcp_f32_e32 v16, v16
	s_nop 0
	v_fma_f32 v21, v16, -2.0, 1.0
	v_mul_f32_e32 v16, 0.5, v12
	v_pk_add_f32 v[12:13], v[20:21], v[132:133]
	v_mov_b32_e32 v132, v14
	v_mul_f32_e32 v13, v16, v13
	v_mul_f32_e32 v12, v12, v13
	v_lshlrev_b32_e32 v13, 16, v17
	v_mul_f32_e32 v16, 0x3d372713, v13
	v_mul_f32_e32 v16, v16, v13
	v_fma_f32 v16, v16, v13, v13
	v_mul_f32_e32 v16, 0x3f4c422a, v16
	v_add_f32_e32 v16, v16, v16
	v_mul_f32_e32 v16, 0x3fb8aa3b, v16
	v_exp_f32_e32 v16, v16
	v_and_b32_e32 v14, 0xffff0000, v17
	v_cvt_pk_bf16_f32 v12, v18, v12
	v_mul_f32_e32 v13, 0.5, v13
	v_add_f32_e32 v16, 1.0, v16
	v_rcp_f32_e32 v16, v16
	s_nop 0
	v_fma_f32 v21, v16, -2.0, 1.0
	v_mul_f32_e32 v16, 0x3d372713, v14
	v_mul_f32_e32 v16, v16, v14
	v_fma_f32 v16, v16, v14, v14
	v_mul_f32_e32 v16, 0x3f4c422a, v16
	v_add_f32_e32 v16, v16, v16
	v_mul_f32_e32 v16, 0x3fb8aa3b, v16
	v_exp_f32_e32 v16, v16
	v_pk_add_f32 v[18:19], v[20:21], v[132:133]
	v_mov_b32_e32 v132, v15
	v_mul_f32_e32 v13, v13, v19
	v_add_f32_e32 v16, 1.0, v16
	v_rcp_f32_e32 v16, v16
	v_mul_f32_e32 v13, v18, v13
	v_fma_f32 v21, v16, -2.0, 1.0
	v_mul_f32_e32 v16, 0.5, v14
	v_pk_add_f32 v[14:15], v[20:21], v[132:133]
	v_mov_b32_e32 v132, v8
	v_mul_f32_e32 v15, v16, v15
	v_mul_f32_e32 v14, v14, v15
	v_cvt_pk_bf16_f32 v13, v13, v14
	global_store_dwordx2 v[22:23], v[12:13], off offset:1568
	s_waitcnt vmcnt(3)
	v_mov_b32_e32 v12, v112
	v_mov_b32_e32 v13, v113
	v_lshlrev_b32_e32 v14, 16, v12
	v_mul_f32_e32 v15, 0x3d372713, v14
	v_mul_f32_e32 v15, v15, v14
	v_fma_f32 v15, v15, v14, v14
	v_mul_f32_e32 v15, 0x3f4c422a, v15
	v_add_f32_e32 v15, v15, v15
	v_mul_f32_e32 v15, 0x3fb8aa3b, v15
	v_exp_f32_e32 v15, v15
	v_mul_f32_e32 v16, 0.5, v14
	v_add_f32_e32 v15, 1.0, v15
	v_rcp_f32_e32 v15, v15
	s_nop 0
	v_fma_f32 v21, v15, -2.0, 1.0
	v_pk_add_f32 v[14:15], v[20:21], v[132:133]
	v_mov_b32_e32 v132, v9
	v_mul_f32_e32 v8, v16, v15
	v_mul_f32_e32 v14, v14, v8
	v_and_b32_e32 v8, 0xffff0000, v12
	v_mul_f32_e32 v12, 0x3d372713, v8
	v_mul_f32_e32 v12, v12, v8
	v_fma_f32 v12, v12, v8, v8
	v_mul_f32_e32 v12, 0x3f4c422a, v12
	v_add_f32_e32 v12, v12, v12
	v_mul_f32_e32 v12, 0x3fb8aa3b, v12
	v_exp_f32_e32 v12, v12
	s_nop 0
	v_add_f32_e32 v12, 1.0, v12
	v_rcp_f32_e32 v12, v12
	s_nop 0
	v_fma_f32 v21, v12, -2.0, 1.0
	v_mul_f32_e32 v12, 0.5, v8
	v_pk_add_f32 v[8:9], v[20:21], v[132:133]
	v_mov_b32_e32 v132, v10
	v_mul_f32_e32 v9, v12, v9
	v_mul_f32_e32 v8, v8, v9
	v_lshlrev_b32_e32 v9, 16, v13
	v_mul_f32_e32 v12, 0x3d372713, v9
	v_mul_f32_e32 v12, v12, v9
	v_fma_f32 v12, v12, v9, v9
	v_mul_f32_e32 v12, 0x3f4c422a, v12
	v_add_f32_e32 v12, v12, v12
	v_mul_f32_e32 v12, 0x3fb8aa3b, v12
	v_exp_f32_e32 v12, v12
	v_and_b32_e32 v10, 0xffff0000, v13
	v_cvt_pk_bf16_f32 v8, v14, v8
	v_mul_f32_e32 v9, 0.5, v9
	v_add_f32_e32 v12, 1.0, v12
	v_rcp_f32_e32 v12, v12
	s_nop 0
	v_fma_f32 v21, v12, -2.0, 1.0
	v_mul_f32_e32 v12, 0x3d372713, v10
	v_mul_f32_e32 v12, v12, v10
	v_fma_f32 v12, v12, v10, v10
	v_mul_f32_e32 v12, 0x3f4c422a, v12
	v_add_f32_e32 v12, v12, v12
	v_mul_f32_e32 v12, 0x3fb8aa3b, v12
	v_exp_f32_e32 v12, v12
	v_pk_add_f32 v[14:15], v[20:21], v[132:133]
	v_mov_b32_e32 v132, v11
	v_mul_f32_e32 v9, v9, v15
	v_add_f32_e32 v12, 1.0, v12
	v_rcp_f32_e32 v12, v12
	v_mul_f32_e32 v9, v14, v9
	v_fma_f32 v21, v12, -2.0, 1.0
	v_mul_f32_e32 v12, 0.5, v10
	v_pk_add_f32 v[10:11], v[20:21], v[132:133]
	v_mov_b32_e32 v132, v4
	v_mul_f32_e32 v11, v12, v11
	v_mul_f32_e32 v10, v10, v11
	v_cvt_pk_bf16_f32 v9, v9, v10
	global_store_dwordx2 v[22:23], v[8:9], off offset:1600
	s_waitcnt vmcnt(3)
	v_mov_b32_e32 v8, v114
	v_mov_b32_e32 v9, v115
	v_lshlrev_b32_e32 v10, 16, v8
	v_mul_f32_e32 v11, 0x3d372713, v10
	v_mul_f32_e32 v11, v11, v10
	v_fma_f32 v11, v11, v10, v10
	v_mul_f32_e32 v11, 0x3f4c422a, v11
	v_add_f32_e32 v11, v11, v11
	v_mul_f32_e32 v11, 0x3fb8aa3b, v11
	v_exp_f32_e32 v11, v11
	v_mul_f32_e32 v12, 0.5, v10
	v_add_f32_e32 v11, 1.0, v11
	v_rcp_f32_e32 v11, v11
	s_nop 0
	v_fma_f32 v21, v11, -2.0, 1.0
	v_pk_add_f32 v[10:11], v[20:21], v[132:133]
	v_mov_b32_e32 v132, v5
	v_mul_f32_e32 v4, v12, v11
	v_mul_f32_e32 v10, v10, v4
	v_and_b32_e32 v4, 0xffff0000, v8
	v_mul_f32_e32 v8, 0x3d372713, v4
	v_mul_f32_e32 v8, v8, v4
	v_fma_f32 v8, v8, v4, v4
	v_mul_f32_e32 v8, 0x3f4c422a, v8
	v_add_f32_e32 v8, v8, v8
	v_mul_f32_e32 v8, 0x3fb8aa3b, v8
	v_exp_f32_e32 v8, v8
	s_nop 0
	v_add_f32_e32 v8, 1.0, v8
	v_rcp_f32_e32 v8, v8
	s_nop 0
	v_fma_f32 v21, v8, -2.0, 1.0
	v_mul_f32_e32 v8, 0.5, v4
	v_pk_add_f32 v[4:5], v[20:21], v[132:133]
	v_mov_b32_e32 v132, v6
	v_mul_f32_e32 v5, v8, v5
	v_mul_f32_e32 v4, v4, v5
	v_lshlrev_b32_e32 v5, 16, v9
	v_mul_f32_e32 v8, 0x3d372713, v5
	v_mul_f32_e32 v8, v8, v5
	v_fma_f32 v8, v8, v5, v5
	v_mul_f32_e32 v8, 0x3f4c422a, v8
	v_add_f32_e32 v8, v8, v8
	v_mul_f32_e32 v8, 0x3fb8aa3b, v8
	v_exp_f32_e32 v8, v8
	v_and_b32_e32 v6, 0xffff0000, v9
	v_cvt_pk_bf16_f32 v4, v10, v4
	v_mul_f32_e32 v5, 0.5, v5
	v_add_f32_e32 v8, 1.0, v8
	v_rcp_f32_e32 v8, v8
	s_nop 0
	v_fma_f32 v21, v8, -2.0, 1.0
	v_mul_f32_e32 v8, 0x3d372713, v6
	v_mul_f32_e32 v8, v8, v6
	v_fma_f32 v8, v8, v6, v6
	v_mul_f32_e32 v8, 0x3f4c422a, v8
	v_add_f32_e32 v8, v8, v8
	v_mul_f32_e32 v8, 0x3fb8aa3b, v8
	v_exp_f32_e32 v8, v8
	v_pk_add_f32 v[10:11], v[20:21], v[132:133]
	v_mov_b32_e32 v132, v7
	v_mul_f32_e32 v5, v5, v11
	v_add_f32_e32 v8, 1.0, v8
	v_rcp_f32_e32 v8, v8
	v_mul_f32_e32 v5, v10, v5
	v_fma_f32 v21, v8, -2.0, 1.0
	v_mul_f32_e32 v8, 0.5, v6
	v_pk_add_f32 v[6:7], v[20:21], v[132:133]
	s_nop 0
	v_mul_f32_e32 v7, v8, v7
	v_mul_f32_e32 v6, v6, v7
	v_cvt_pk_bf16_f32 v5, v5, v6
	global_store_dwordx2 v[22:23], v[4:5], off offset:1632
	s_cbranch_scc0 .LBB0_285

.LBB0_358:
	s_waitcnt vmcnt(1)
	v_add_co_u32_e32 v8, vcc, 0x8000000, v100
	s_nop 1
	v_addc_co_u32_e32 v9, vcc, 0, v101, vcc
	s_waitcnt lgkmcnt(0)
	global_load_dwordx4 v[4:7], v[8:9], off
	global_load_dwordx4 v[20:23], v[8:9], off offset:1024
	s_add_i32 s8, s60, 1
	s_ashr_i32 s9, s8, 31
	s_lshl_b64 s[8:9], s[8:9], 11
	v_lshl_add_u64 v[244:245], v[86:87], 0, s[8:9]
	global_load_dwordx4 v[228:231], v[244:245], off
	global_load_dwordx4 v[232:235], v[244:245], off offset:1024
	global_load_dwordx4 v[236:239], v[244:245], off offset:2048
	global_load_dwordx4 v[240:243], v[244:245], off offset:3072
	s_waitcnt vmcnt(5)
	v_lshlrev_b32_e32 v16, 16, v4
	v_and_b32_e32 v17, 0xffff0000, v4
	v_lshlrev_b32_e32 v18, 16, v5
	v_and_b32_e32 v19, 0xffff0000, v5
	v_lshlrev_b32_e32 v12, 16, v6
	v_and_b32_e32 v13, 0xffff0000, v6
	v_lshlrev_b32_e32 v14, 16, v7
	v_and_b32_e32 v15, 0xffff0000, v7
	s_waitcnt vmcnt(4)
	v_lshlrev_b32_e32 v8, 16, v20
	v_and_b32_e32 v9, 0xffff0000, v20
	v_lshlrev_b32_e32 v10, 16, v21
	v_and_b32_e32 v11, 0xffff0000, v21
	v_lshlrev_b32_e32 v4, 16, v22
	v_and_b32_e32 v5, 0xffff0000, v22
	v_lshlrev_b32_e32 v6, 16, v23
	v_and_b32_e32 v7, 0xffff0000, v23
.LBB0_359:
	s_brev_b32 s2, 48
	v_add_co_u32_e32 v24, vcc, s2, v100
	v_cndmask_b32_e64 v28, 0, 1, s[22:23]
	s_nop 0
	v_addc_co_u32_e32 v25, vcc, 0, v101, vcc
	global_load_dwordx4 v[20:23], v[24:25], off
	s_nop 0
	global_load_dwordx4 v[24:27], v[24:25], off offset:1024
	s_add_i32 s8, s60, 1
	s_ashr_i32 s9, s8, 31
	s_lshl_b64 s[8:9], s[8:9], 11
	v_lshl_add_u64 v[200:201], v[0:1], 0, s[8:9]
	s_mov_b64 s[8:9], 0x1000
	v_lshl_add_u64 v[202:203], v[200:201], 0, s[8:9]
	global_load_dwordx4 v[204:207], v[200:201], off
	global_load_dwordx4 v[208:211], v[200:201], off offset:1024
	global_load_dwordx4 v[212:215], v[200:201], off offset:2048
	global_load_dwordx4 v[216:219], v[200:201], off offset:3072
	global_load_dwordx4 v[220:223], v[202:203], off
	global_load_dwordx4 v[224:227], v[202:203], off offset:1024
	v_cmp_ne_u32_e64 s[42:43], 1, v28
	s_andn2_b64 vcc, exec, s[22:23]
	s_waitcnt vmcnt(7)
	v_lshlrev_b32_e32 v114, 16, v20
	v_and_b32_e32 v115, 0xffff0000, v20
	v_lshlrev_b32_e32 v116, 16, v21
	v_and_b32_e32 v117, 0xffff0000, v21
	v_lshlrev_b32_e32 v110, 16, v22
	v_and_b32_e32 v111, 0xffff0000, v22
	v_lshlrev_b32_e32 v112, 16, v23
	v_and_b32_e32 v113, 0xffff0000, v23
	s_waitcnt vmcnt(6)
	v_lshlrev_b32_e32 v106, 16, v24
	v_and_b32_e32 v107, 0xffff0000, v24
	v_lshlrev_b32_e32 v108, 16, v25
	v_and_b32_e32 v109, 0xffff0000, v25
	v_lshlrev_b32_e32 v102, 16, v26
	v_and_b32_e32 v103, 0xffff0000, v26
	v_lshlrev_b32_e32 v104, 16, v27
	v_and_b32_e32 v105, 0xffff0000, v27
	s_cbranch_vccnz .LBB0_361
	v_lshl_add_u64 v[24:25], s[48:49], 0, v[94:95]
	global_load_dwordx4 v[20:23], v[24:25], off offset:-1024
	s_waitcnt vmcnt(0)
	v_lshlrev_b32_e32 v26, 16, v20
	v_and_b32_e32 v27, 0xffff0000, v20
	v_lshlrev_b32_e32 v28, 16, v21
	v_and_b32_e32 v29, 0xffff0000, v21
	v_mul_f32_e32 v20, 0xbfb8aa3b, v26
	v_mul_f32_e32 v21, 0xbfb8aa3b, v27
	v_exp_f32_e32 v20, v20
	v_exp_f32_e32 v21, v21
	v_lshlrev_b32_e32 v30, 16, v22
	v_and_b32_e32 v22, 0xffff0000, v22
	v_add_f32_e32 v20, 1.0, v20
	v_add_f32_e32 v21, 1.0, v21
	v_rcp_f32_e32 v20, v20
	v_rcp_f32_e32 v21, v21
	v_lshlrev_b32_e32 v31, 16, v23
	v_and_b32_e32 v23, 0xffff0000, v23
	v_pk_mul_f32 v[114:115], v[20:21], v[114:115]
	v_mul_f32_e32 v20, 0xbfb8aa3b, v28
	v_mul_f32_e32 v21, 0xbfb8aa3b, v29
	v_exp_f32_e32 v20, v20
	v_exp_f32_e32 v21, v21
	v_add_f32_e32 v20, 1.0, v20
	v_add_f32_e32 v21, 1.0, v21
	v_rcp_f32_e32 v20, v20
	v_rcp_f32_e32 v21, v21
	s_nop 0
	v_pk_mul_f32 v[116:117], v[20:21], v[116:117]
	v_mul_f32_e32 v20, 0xbfb8aa3b, v30
	v_mul_f32_e32 v21, 0xbfb8aa3b, v22
	v_exp_f32_e32 v20, v20
	v_exp_f32_e32 v21, v21
	v_add_f32_e32 v20, 1.0, v20
	v_add_f32_e32 v21, 1.0, v21
	v_rcp_f32_e32 v20, v20
	v_rcp_f32_e32 v21, v21
	s_nop 0
	v_pk_mul_f32 v[110:111], v[20:21], v[110:111]
	v_mul_f32_e32 v20, 0xbfb8aa3b, v31
	v_mul_f32_e32 v21, 0xbfb8aa3b, v23
	v_exp_f32_e32 v20, v20
	v_exp_f32_e32 v21, v21
	v_add_f32_e32 v20, 1.0, v20
	v_add_f32_e32 v21, 1.0, v21
	v_rcp_f32_e32 v20, v20
	v_rcp_f32_e32 v21, v21
	s_nop 0
	v_pk_mul_f32 v[112:113], v[20:21], v[112:113]
	global_load_dwordx4 v[20:23], v[24:25], off
	s_waitcnt vmcnt(0)
	v_lshlrev_b32_e32 v24, 16, v20
	v_and_b32_e32 v25, 0xffff0000, v20
	v_lshlrev_b32_e32 v26, 16, v21
	v_and_b32_e32 v27, 0xffff0000, v21
	v_mul_f32_e32 v20, 0xbfb8aa3b, v24
	v_mul_f32_e32 v21, 0xbfb8aa3b, v25
	v_exp_f32_e32 v20, v20
	v_exp_f32_e32 v21, v21
	v_lshlrev_b32_e32 v28, 16, v22
	v_and_b32_e32 v22, 0xffff0000, v22
	v_add_f32_e32 v20, 1.0, v20
	v_add_f32_e32 v21, 1.0, v21
	v_rcp_f32_e32 v20, v20
	v_rcp_f32_e32 v21, v21
	v_lshlrev_b32_e32 v29, 16, v23
	v_and_b32_e32 v23, 0xffff0000, v23
	v_pk_mul_f32 v[106:107], v[20:21], v[106:107]
	v_mul_f32_e32 v20, 0xbfb8aa3b, v26
	v_mul_f32_e32 v21, 0xbfb8aa3b, v27
	v_exp_f32_e32 v20, v20
	v_exp_f32_e32 v21, v21
	v_add_f32_e32 v20, 1.0, v20
	v_add_f32_e32 v21, 1.0, v21
	v_rcp_f32_e32 v20, v20
	v_rcp_f32_e32 v21, v21
	s_nop 0
	v_pk_mul_f32 v[108:109], v[20:21], v[108:109]
	v_mul_f32_e32 v20, 0xbfb8aa3b, v28
	v_mul_f32_e32 v21, 0xbfb8aa3b, v22
	v_exp_f32_e32 v20, v20
	v_exp_f32_e32 v21, v21
	v_add_f32_e32 v20, 1.0, v20
	v_add_f32_e32 v21, 1.0, v21
	v_rcp_f32_e32 v20, v20
	v_rcp_f32_e32 v21, v21
	s_nop 0
	v_pk_mul_f32 v[102:103], v[20:21], v[102:103]
	v_mul_f32_e32 v20, 0xbfb8aa3b, v29
	v_mul_f32_e32 v21, 0xbfb8aa3b, v23
	v_exp_f32_e32 v20, v20
	v_exp_f32_e32 v21, v21
	v_add_f32_e32 v20, 1.0, v20
	v_add_f32_e32 v21, 1.0, v21
	v_rcp_f32_e32 v20, v20
	v_rcp_f32_e32 v21, v21
	s_nop 0
	v_pk_mul_f32 v[104:105], v[20:21], v[104:105]

.LBB0_363:
	s_lshl_b64 s[52:53], s[2:3], 11
	s_waitcnt vmcnt(0)
	v_mov_b32_e32 v24, v228
	v_mov_b32_e32 v25, v229
	v_mov_b32_e32 v26, v230
	v_mov_b32_e32 v27, v231
	v_mov_b32_e32 v32, v232
	v_mov_b32_e32 v33, v233
	v_mov_b32_e32 v34, v234
	v_mov_b32_e32 v35, v235
	v_lshlrev_b32_e32 v20, 16, v24
	v_and_b32_e32 v21, 0xffff0000, v24
	v_lshlrev_b32_e32 v22, 16, v25
	v_and_b32_e32 v23, 0xffff0000, v25
	v_lshlrev_b32_e32 v24, 16, v26
	v_and_b32_e32 v25, 0xffff0000, v26
	v_lshlrev_b32_e32 v26, 16, v27
	v_and_b32_e32 v27, 0xffff0000, v27
	s_waitcnt vmcnt(0)
	v_lshlrev_b32_e32 v28, 16, v32
	v_and_b32_e32 v29, 0xffff0000, v32
	v_lshlrev_b32_e32 v30, 16, v33
	v_and_b32_e32 v31, 0xffff0000, v33
	v_lshlrev_b32_e32 v32, 16, v34
	v_and_b32_e32 v33, 0xffff0000, v34
	v_lshlrev_b32_e32 v34, 16, v35
	v_and_b32_e32 v35, 0xffff0000, v35
.LBB0_364:
	s_and_b64 vcc, exec, s[42:43]
	s_waitcnt vmcnt(0)
	v_mov_b32_e32 v36, v204
	v_mov_b32_e32 v37, v205
	v_mov_b32_e32 v38, v206
	v_mov_b32_e32 v39, v207
	v_mov_b32_e32 v40, v208
	v_mov_b32_e32 v41, v209
	v_mov_b32_e32 v42, v210
	v_mov_b32_e32 v43, v211
	v_lshlrev_b32_e32 v130, 16, v36
	v_and_b32_e32 v131, 0xffff0000, v36
	v_lshlrev_b32_e32 v140, 16, v37
	v_and_b32_e32 v141, 0xffff0000, v37
	v_lshlrev_b32_e32 v118, 16, v38
	v_and_b32_e32 v119, 0xffff0000, v38
	v_lshlrev_b32_e32 v120, 16, v39
	v_and_b32_e32 v121, 0xffff0000, v39
	s_waitcnt vmcnt(0)
	v_lshlrev_b32_e32 v122, 16, v40
	v_and_b32_e32 v123, 0xffff0000, v40
	v_lshlrev_b32_e32 v124, 16, v41
	v_and_b32_e32 v125, 0xffff0000, v41
	v_lshlrev_b32_e32 v126, 16, v42
	v_and_b32_e32 v127, 0xffff0000, v42
	v_lshlrev_b32_e32 v128, 16, v43
	v_and_b32_e32 v129, 0xffff0000, v43
	s_cbranch_vccnz .LBB0_366
	v_lshl_add_u64 v[40:41], v[88:89], 0, s[52:53]
	global_load_dwordx4 v[36:39], v[40:41], off
	s_waitcnt vmcnt(0)
	v_lshlrev_b32_e32 v42, 16, v36
	v_and_b32_e32 v43, 0xffff0000, v36
	v_lshlrev_b32_e32 v44, 16, v37
	v_and_b32_e32 v45, 0xffff0000, v37
	v_mul_f32_e32 v36, 0xbfb8aa3b, v42
	v_mul_f32_e32 v37, 0xbfb8aa3b, v43
	v_exp_f32_e32 v36, v36
	v_exp_f32_e32 v37, v37
	v_lshlrev_b32_e32 v46, 16, v38
	v_and_b32_e32 v38, 0xffff0000, v38
	v_add_f32_e32 v36, 1.0, v36
	v_add_f32_e32 v37, 1.0, v37
	v_rcp_f32_e32 v36, v36
	v_rcp_f32_e32 v37, v37
	v_lshlrev_b32_e32 v47, 16, v39
	v_and_b32_e32 v39, 0xffff0000, v39
	v_pk_mul_f32 v[130:131], v[36:37], v[130:131]
	v_mul_f32_e32 v36, 0xbfb8aa3b, v44
	v_mul_f32_e32 v37, 0xbfb8aa3b, v45
	v_exp_f32_e32 v36, v36
	v_exp_f32_e32 v37, v37
	v_add_f32_e32 v36, 1.0, v36
	v_add_f32_e32 v37, 1.0, v37
	v_rcp_f32_e32 v36, v36
	v_rcp_f32_e32 v37, v37
	s_nop 0
	v_pk_mul_f32 v[140:141], v[36:37], v[140:141]
	v_mul_f32_e32 v36, 0xbfb8aa3b, v46
	v_mul_f32_e32 v37, 0xbfb8aa3b, v38
	v_exp_f32_e32 v36, v36
	v_exp_f32_e32 v37, v37
	v_add_f32_e32 v36, 1.0, v36
	v_add_f32_e32 v37, 1.0, v37
	v_rcp_f32_e32 v36, v36
	v_rcp_f32_e32 v37, v37
	s_nop 0
	v_pk_mul_f32 v[118:119], v[36:37], v[118:119]
	v_mul_f32_e32 v36, 0xbfb8aa3b, v47
	v_mul_f32_e32 v37, 0xbfb8aa3b, v39
	v_exp_f32_e32 v36, v36
	v_exp_f32_e32 v37, v37
	v_add_f32_e32 v36, 1.0, v36
	v_add_f32_e32 v37, 1.0, v37
	v_rcp_f32_e32 v36, v36
	v_rcp_f32_e32 v37, v37
	s_nop 0
	v_pk_mul_f32 v[120:121], v[36:37], v[120:121]
	global_load_dwordx4 v[36:39], v[40:41], off offset:1024
	s_waitcnt vmcnt(0)
	v_lshlrev_b32_e32 v40, 16, v36
	v_and_b32_e32 v41, 0xffff0000, v36
	v_lshlrev_b32_e32 v42, 16, v37
	v_and_b32_e32 v43, 0xffff0000, v37
	v_mul_f32_e32 v36, 0xbfb8aa3b, v40
	v_mul_f32_e32 v37, 0xbfb8aa3b, v41
	v_exp_f32_e32 v36, v36
	v_exp_f32_e32 v37, v37
	v_lshlrev_b32_e32 v44, 16, v38
	v_and_b32_e32 v38, 0xffff0000, v38
	v_add_f32_e32 v36, 1.0, v36
	v_add_f32_e32 v37, 1.0, v37
	v_rcp_f32_e32 v36, v36
	v_rcp_f32_e32 v37, v37
	v_lshlrev_b32_e32 v45, 16, v39
	v_and_b32_e32 v39, 0xffff0000, v39
	v_pk_mul_f32 v[122:123], v[36:37], v[122:123]
	v_mul_f32_e32 v36, 0xbfb8aa3b, v42
	v_mul_f32_e32 v37, 0xbfb8aa3b, v43
	v_exp_f32_e32 v36, v36
	v_exp_f32_e32 v37, v37
	v_add_f32_e32 v36, 1.0, v36
	v_add_f32_e32 v37, 1.0, v37
	v_rcp_f32_e32 v36, v36
	v_rcp_f32_e32 v37, v37
	s_nop 0
	v_pk_mul_f32 v[124:125], v[36:37], v[124:125]
	v_mul_f32_e32 v36, 0xbfb8aa3b, v44
	v_mul_f32_e32 v37, 0xbfb8aa3b, v38
	v_exp_f32_e32 v36, v36
	v_exp_f32_e32 v37, v37
	v_add_f32_e32 v36, 1.0, v36
	v_add_f32_e32 v37, 1.0, v37
	v_rcp_f32_e32 v36, v36
	v_rcp_f32_e32 v37, v37
	s_nop 0
	v_pk_mul_f32 v[126:127], v[36:37], v[126:127]
	v_mul_f32_e32 v36, 0xbfb8aa3b, v45
	v_mul_f32_e32 v37, 0xbfb8aa3b, v39
	v_exp_f32_e32 v36, v36
	v_exp_f32_e32 v37, v37
	v_add_f32_e32 v36, 1.0, v36
	v_add_f32_e32 v37, 1.0, v37
	v_rcp_f32_e32 v36, v36
	v_rcp_f32_e32 v37, v37
	s_nop 0
	v_pk_mul_f32 v[128:129], v[36:37], v[128:129]

.LBB0_368:
	s_lshl_b64 s[56:57], s[54:55], 11
	s_waitcnt vmcnt(0)
	v_mov_b32_e32 v40, v236
	v_mov_b32_e32 v41, v237
	v_mov_b32_e32 v42, v238
	v_mov_b32_e32 v43, v239
	v_mov_b32_e32 v48, v240
	v_mov_b32_e32 v49, v241
	v_mov_b32_e32 v50, v242
	v_mov_b32_e32 v51, v243
	v_lshlrev_b32_e32 v36, 16, v40
	v_and_b32_e32 v37, 0xffff0000, v40
	v_lshlrev_b32_e32 v38, 16, v41
	v_and_b32_e32 v39, 0xffff0000, v41
	v_lshlrev_b32_e32 v40, 16, v42
	v_and_b32_e32 v41, 0xffff0000, v42
	v_lshlrev_b32_e32 v42, 16, v43
	v_and_b32_e32 v43, 0xffff0000, v43
	s_waitcnt vmcnt(0)
	v_lshlrev_b32_e32 v44, 16, v48
	v_and_b32_e32 v45, 0xffff0000, v48
	v_lshlrev_b32_e32 v46, 16, v49
	v_and_b32_e32 v47, 0xffff0000, v49
	v_lshlrev_b32_e32 v48, 16, v50
	v_and_b32_e32 v49, 0xffff0000, v50
	v_lshlrev_b32_e32 v50, 16, v51
	v_and_b32_e32 v51, 0xffff0000, v51
.LBB0_369:
	s_and_b64 vcc, exec, s[42:43]
	s_waitcnt vmcnt(0)
	v_mov_b32_e32 v52, v212
	v_mov_b32_e32 v53, v213
	v_mov_b32_e32 v54, v214
	v_mov_b32_e32 v55, v215
	v_mov_b32_e32 v56, v216
	v_mov_b32_e32 v57, v217
	v_mov_b32_e32 v58, v218
	v_mov_b32_e32 v59, v219
	v_lshlrev_b32_e32 v154, 16, v52
	v_and_b32_e32 v155, 0xffff0000, v52
	v_lshlrev_b32_e32 v156, 16, v53
	v_and_b32_e32 v157, 0xffff0000, v53
	v_lshlrev_b32_e32 v142, 16, v54
	v_and_b32_e32 v143, 0xffff0000, v54
	v_lshlrev_b32_e32 v144, 16, v55
	v_and_b32_e32 v145, 0xffff0000, v55
	s_waitcnt vmcnt(0)
	v_lshlrev_b32_e32 v146, 16, v56
	v_and_b32_e32 v147, 0xffff0000, v56
	v_lshlrev_b32_e32 v148, 16, v57
	v_and_b32_e32 v149, 0xffff0000, v57
	v_lshlrev_b32_e32 v150, 16, v58
	v_and_b32_e32 v151, 0xffff0000, v58
	v_lshlrev_b32_e32 v152, 16, v59
	v_and_b32_e32 v153, 0xffff0000, v59
	s_cbranch_vccnz .LBB0_371
	v_lshl_add_u64 v[56:57], v[88:89], 0, s[56:57]
	global_load_dwordx4 v[52:55], v[56:57], off
	s_waitcnt vmcnt(0)
	v_lshlrev_b32_e32 v58, 16, v52
	v_and_b32_e32 v59, 0xffff0000, v52
	v_lshlrev_b32_e32 v60, 16, v53
	v_and_b32_e32 v61, 0xffff0000, v53
	v_mul_f32_e32 v52, 0xbfb8aa3b, v58
	v_mul_f32_e32 v53, 0xbfb8aa3b, v59
	v_exp_f32_e32 v52, v52
	v_exp_f32_e32 v53, v53
	v_lshlrev_b32_e32 v62, 16, v54
	v_and_b32_e32 v54, 0xffff0000, v54
	v_add_f32_e32 v52, 1.0, v52
	v_add_f32_e32 v53, 1.0, v53
	v_rcp_f32_e32 v52, v52
	v_rcp_f32_e32 v53, v53
	v_lshlrev_b32_e32 v63, 16, v55
	v_and_b32_e32 v55, 0xffff0000, v55
	v_pk_mul_f32 v[154:155], v[52:53], v[154:155]
	v_mul_f32_e32 v52, 0xbfb8aa3b, v60
	v_mul_f32_e32 v53, 0xbfb8aa3b, v61
	v_exp_f32_e32 v52, v52
	v_exp_f32_e32 v53, v53
	v_add_f32_e32 v52, 1.0, v52
	v_add_f32_e32 v53, 1.0, v53
	v_rcp_f32_e32 v52, v52
	v_rcp_f32_e32 v53, v53
	s_nop 0
	v_pk_mul_f32 v[156:157], v[52:53], v[156:157]
	v_mul_f32_e32 v52, 0xbfb8aa3b, v62
	v_mul_f32_e32 v53, 0xbfb8aa3b, v54
	v_exp_f32_e32 v52, v52
	v_exp_f32_e32 v53, v53
	v_add_f32_e32 v52, 1.0, v52
	v_add_f32_e32 v53, 1.0, v53
	v_rcp_f32_e32 v52, v52
	v_rcp_f32_e32 v53, v53
	s_nop 0
	v_pk_mul_f32 v[142:143], v[52:53], v[142:143]
	v_mul_f32_e32 v52, 0xbfb8aa3b, v63
	v_mul_f32_e32 v53, 0xbfb8aa3b, v55
	v_exp_f32_e32 v52, v52
	v_exp_f32_e32 v53, v53
	v_add_f32_e32 v52, 1.0, v52
	v_add_f32_e32 v53, 1.0, v53
	v_rcp_f32_e32 v52, v52
	v_rcp_f32_e32 v53, v53
	s_nop 0
	v_pk_mul_f32 v[144:145], v[52:53], v[144:145]
	global_load_dwordx4 v[52:55], v[56:57], off offset:1024
	s_waitcnt vmcnt(0)
	v_lshlrev_b32_e32 v56, 16, v52
	v_and_b32_e32 v57, 0xffff0000, v52
	v_lshlrev_b32_e32 v58, 16, v53
	v_and_b32_e32 v59, 0xffff0000, v53
	v_mul_f32_e32 v52, 0xbfb8aa3b, v56
	v_mul_f32_e32 v53, 0xbfb8aa3b, v57
	v_exp_f32_e32 v52, v52
	v_exp_f32_e32 v53, v53
	v_lshlrev_b32_e32 v60, 16, v54
	v_and_b32_e32 v54, 0xffff0000, v54
	v_add_f32_e32 v52, 1.0, v52
	v_add_f32_e32 v53, 1.0, v53
	v_rcp_f32_e32 v52, v52
	v_rcp_f32_e32 v53, v53
	v_lshlrev_b32_e32 v61, 16, v55
	v_and_b32_e32 v55, 0xffff0000, v55
	v_pk_mul_f32 v[146:147], v[52:53], v[146:147]
	v_mul_f32_e32 v52, 0xbfb8aa3b, v58
	v_mul_f32_e32 v53, 0xbfb8aa3b, v59
	v_exp_f32_e32 v52, v52
	v_exp_f32_e32 v53, v53
	v_add_f32_e32 v52, 1.0, v52
	v_add_f32_e32 v53, 1.0, v53
	v_rcp_f32_e32 v52, v52
	v_rcp_f32_e32 v53, v53
	s_nop 0
	v_pk_mul_f32 v[148:149], v[52:53], v[148:149]
	v_mul_f32_e32 v52, 0xbfb8aa3b, v60
	v_mul_f32_e32 v53, 0xbfb8aa3b, v54
	v_exp_f32_e32 v52, v52
	v_exp_f32_e32 v53, v53
	v_add_f32_e32 v52, 1.0, v52
	v_add_f32_e32 v53, 1.0, v53
	v_rcp_f32_e32 v52, v52
	v_rcp_f32_e32 v53, v53
	s_nop 0
	v_pk_mul_f32 v[150:151], v[52:53], v[150:151]
	v_mul_f32_e32 v52, 0xbfb8aa3b, v61
	v_mul_f32_e32 v53, 0xbfb8aa3b, v55
	v_exp_f32_e32 v52, v52
	v_exp_f32_e32 v53, v53
	v_add_f32_e32 v52, 1.0, v52
	v_add_f32_e32 v53, 1.0, v53
	v_rcp_f32_e32 v52, v52
	v_rcp_f32_e32 v53, v53
	s_nop 0
	v_pk_mul_f32 v[152:153], v[52:53], v[152:153]

.LBB0_374:
	s_and_b64 vcc, exec, s[42:43]
	s_waitcnt vmcnt(0)
	v_mov_b32_e32 v68, v220
	v_mov_b32_e32 v69, v221
	v_mov_b32_e32 v70, v222
	v_mov_b32_e32 v71, v223
	v_mov_b32_e32 v72, v224
	v_mov_b32_e32 v73, v225
	v_mov_b32_e32 v74, v226
	v_mov_b32_e32 v75, v227
	v_lshlrev_b32_e32 v170, 16, v68
	v_and_b32_e32 v171, 0xffff0000, v68
	v_lshlrev_b32_e32 v172, 16, v69
	v_and_b32_e32 v173, 0xffff0000, v69
	v_lshlrev_b32_e32 v158, 16, v70
	v_and_b32_e32 v159, 0xffff0000, v70
	v_lshlrev_b32_e32 v160, 16, v71
	v_and_b32_e32 v161, 0xffff0000, v71
	s_waitcnt vmcnt(0)
	v_lshlrev_b32_e32 v162, 16, v72
	v_and_b32_e32 v163, 0xffff0000, v72
	v_lshlrev_b32_e32 v164, 16, v73
	v_and_b32_e32 v165, 0xffff0000, v73
	v_lshlrev_b32_e32 v166, 16, v74
	v_and_b32_e32 v167, 0xffff0000, v74
	v_lshlrev_b32_e32 v168, 16, v75
	v_and_b32_e32 v169, 0xffff0000, v75
	s_cbranch_vccnz .LBB0_376
	v_lshl_add_u64 v[72:73], v[88:89], 0, s[58:59]
	global_load_dwordx4 v[68:71], v[72:73], off
	s_waitcnt vmcnt(0)
	v_lshlrev_b32_e32 v74, 16, v68
	v_and_b32_e32 v75, 0xffff0000, v68
	v_lshlrev_b32_e32 v76, 16, v69
	v_and_b32_e32 v77, 0xffff0000, v69
	v_mul_f32_e32 v68, 0xbfb8aa3b, v74
	v_mul_f32_e32 v69, 0xbfb8aa3b, v75
	v_exp_f32_e32 v68, v68
	v_exp_f32_e32 v69, v69
	v_lshlrev_b32_e32 v78, 16, v70
	v_and_b32_e32 v70, 0xffff0000, v70
	v_add_f32_e32 v68, 1.0, v68
	v_add_f32_e32 v69, 1.0, v69
	v_rcp_f32_e32 v68, v68
	v_rcp_f32_e32 v69, v69
	v_lshlrev_b32_e32 v79, 16, v71
	v_and_b32_e32 v71, 0xffff0000, v71
	v_pk_mul_f32 v[170:171], v[68:69], v[170:171]
	v_mul_f32_e32 v68, 0xbfb8aa3b, v76
	v_mul_f32_e32 v69, 0xbfb8aa3b, v77
	v_exp_f32_e32 v68, v68
	v_exp_f32_e32 v69, v69
	v_add_f32_e32 v68, 1.0, v68
	v_add_f32_e32 v69, 1.0, v69
	v_rcp_f32_e32 v68, v68
	v_rcp_f32_e32 v69, v69
	s_nop 0
	v_pk_mul_f32 v[172:173], v[68:69], v[172:173]
	v_mul_f32_e32 v68, 0xbfb8aa3b, v78
	v_mul_f32_e32 v69, 0xbfb8aa3b, v70
	v_exp_f32_e32 v68, v68
	v_exp_f32_e32 v69, v69
	v_add_f32_e32 v68, 1.0, v68
	v_add_f32_e32 v69, 1.0, v69
	v_rcp_f32_e32 v68, v68
	v_rcp_f32_e32 v69, v69
	s_nop 0
	v_pk_mul_f32 v[158:159], v[68:69], v[158:159]
	v_mul_f32_e32 v68, 0xbfb8aa3b, v79
	v_mul_f32_e32 v69, 0xbfb8aa3b, v71
	v_exp_f32_e32 v68, v68
	v_exp_f32_e32 v69, v69
	v_add_f32_e32 v68, 1.0, v68
	v_add_f32_e32 v69, 1.0, v69
	v_rcp_f32_e32 v68, v68
	v_rcp_f32_e32 v69, v69
	s_nop 0
	v_pk_mul_f32 v[160:161], v[68:69], v[160:161]
	global_load_dwordx4 v[68:71], v[72:73], off offset:1024
	s_waitcnt vmcnt(0)
	v_lshlrev_b32_e32 v72, 16, v68
	v_and_b32_e32 v73, 0xffff0000, v68
	v_lshlrev_b32_e32 v74, 16, v69
	v_and_b32_e32 v75, 0xffff0000, v69
	v_mul_f32_e32 v68, 0xbfb8aa3b, v72
	v_mul_f32_e32 v69, 0xbfb8aa3b, v73
	v_exp_f32_e32 v68, v68
	v_exp_f32_e32 v69, v69
	v_lshlrev_b32_e32 v76, 16, v70
	v_and_b32_e32 v70, 0xffff0000, v70
	v_add_f32_e32 v68, 1.0, v68
	v_add_f32_e32 v69, 1.0, v69
	v_rcp_f32_e32 v68, v68
	v_rcp_f32_e32 v69, v69
	v_lshlrev_b32_e32 v77, 16, v71
	v_and_b32_e32 v71, 0xffff0000, v71
	v_pk_mul_f32 v[162:163], v[68:69], v[162:163]
	v_mul_f32_e32 v68, 0xbfb8aa3b, v74
	v_mul_f32_e32 v69, 0xbfb8aa3b, v75
	v_exp_f32_e32 v68, v68
	v_exp_f32_e32 v69, v69
	v_add_f32_e32 v68, 1.0, v68
	v_add_f32_e32 v69, 1.0, v69
	v_rcp_f32_e32 v68, v68
	v_rcp_f32_e32 v69, v69
	s_nop 0
	v_pk_mul_f32 v[164:165], v[68:69], v[164:165]
	v_mul_f32_e32 v68, 0xbfb8aa3b, v76
	v_mul_f32_e32 v69, 0xbfb8aa3b, v70
	v_exp_f32_e32 v68, v68
	v_exp_f32_e32 v69, v69
	v_add_f32_e32 v68, 1.0, v68
	v_add_f32_e32 v69, 1.0, v69
	v_rcp_f32_e32 v68, v68
	v_rcp_f32_e32 v69, v69
	s_nop 0
	v_pk_mul_f32 v[166:167], v[68:69], v[166:167]
	v_mul_f32_e32 v68, 0xbfb8aa3b, v77
	v_mul_f32_e32 v69, 0xbfb8aa3b, v71
	v_exp_f32_e32 v68, v68
	v_exp_f32_e32 v69, v69
	v_add_f32_e32 v68, 1.0, v68
	v_add_f32_e32 v69, 1.0, v69
	v_rcp_f32_e32 v68, v68
	v_rcp_f32_e32 v69, v69
	s_nop 0
	v_pk_mul_f32 v[168:169], v[68:69], v[168:169]
